# nt hint on in-proj P stores only, on top of previous
# speedup vs baseline: 1.0038x; 1.0006x over previous
; __device__ __forceinline__ unsigned cvt_pk_bf16(float lo, float hi) { const f32x2_t v = {lo, hi}; const bf16x2_t b = __builtin_convertvector(v, bf16x2_t); return __builtin_bit_cast(unsigned, b); }
;     __device__ __forceinline__ void operator()(const f32x4 (&acc)[2][2][4][2], const Unit& u, int wr, int wc, int fr, int fq) const {
;         const int row0 = u.pm * BM + wr * 64 + fr; const int col0 = u.pn * BM + wc * 32 + 8 * fq;
; #pragma unroll
;         for (int ai = 0; ai < 2; ++ai)
; #pragma unroll
;             for (int m = 0; m < 4; ++m) { bf16_t* rowp = O + (size_t)u.zo * zsO + (size_t)(row0 + ai * HALF + m * 16) * ldc + col0;
; #pragma unroll
;                 for (int bj = 0; bj < 2; ++bj) { f32x4 v0 = acc[ai][bj][m][0], v1 = acc[ai][bj][m][1];
;                     if (ACT == 2) {
; #pragma unroll
;                         for (int j = 0; j < 4; ++j) { const float a = fmaxf(v0[j], 0.f), b = fmaxf(v1[j], 0.f); v0[j] = a * a; v1[j] = b * b; } }
;                     u32x4 w; w.x = cvt_pk_bf16(v0[0], v0[1]); w.y = cvt_pk_bf16(v0[2], v0[3]); w.z = cvt_pk_bf16(v1[0], v1[1]); w.w = cvt_pk_bf16(v1[2], v1[3]);
;                     *(u32x4*)(rowp + bj * HALF) = w; } }
;     }
.LBB0_319:
	v_lshl_or_b32 v144, s30, 8, v142
	v_lshl_add_u32 v150, s31, 8, v140
	v_ashrrev_i32_e32 v145, 31, v144
	v_mov_b64_e32 v[146:147], s[84:85]
	v_cvt_pk_bf16_f32 v70, v70, v71
	v_cvt_pk_bf16_f32 v71, v72, v73
	v_cvt_pk_bf16_f32 v72, v66, v67
	v_add_u32_e32 v66, 0x80, v150
	v_mad_i64_i32 v[148:149], s[0:1], v150, s91, v[146:147]
	v_lshlrev_b64 v[144:145], 1, v[144:145]
	v_cvt_pk_bf16_f32 v110, v110, v111
	v_cvt_pk_bf16_f32 v111, v112, v113
	v_cvt_pk_bf16_f32 v112, v106, v107
	v_or_b32_e32 v106, 16, v150
	v_mad_i64_i32 v[66:67], s[0:1], v66, s91, v[146:147]
	v_cvt_pk_bf16_f32 v44, v44, v45
	v_cvt_pk_bf16_f32 v45, v46, v47
	v_cvt_pk_bf16_f32 v46, v40, v41
	v_add_u32_e32 v40, 0x90, v150
	v_lshl_add_u64 v[148:149], v[148:149], 0, v[144:145]
	v_cvt_pk_bf16_f32 v113, v108, v109
	v_mad_i64_i32 v[106:107], s[0:1], v106, s91, v[146:147]
	v_cvt_pk_bf16_f32 v94, v94, v95
	v_cvt_pk_bf16_f32 v95, v96, v97
	v_cvt_pk_bf16_f32 v96, v90, v91
	v_or_b32_e32 v90, 32, v150
	v_lshl_add_u64 v[66:67], v[66:67], 0, v[144:145]
	v_cvt_pk_bf16_f32 v47, v42, v43
	v_mad_i64_i32 v[40:41], s[0:1], v40, s91, v[146:147]
	v_cvt_pk_bf16_f32 v28, v28, v29
	v_cvt_pk_bf16_f32 v29, v30, v31
	v_cvt_pk_bf16_f32 v30, v24, v25
	v_add_u32_e32 v24, 0xa0, v150
	global_store_dwordx4 v[148:149], v[110:113], off offset:256 nt
	v_cvt_pk_bf16_f32 v97, v92, v93
	v_mad_i64_i32 v[90:91], s[0:1], v90, s91, v[146:147]
	v_lshl_add_u64 v[110:111], v[106:107], 0, v[144:145]
	v_cvt_pk_bf16_f32 v78, v78, v79
	v_cvt_pk_bf16_f32 v79, v80, v81
	v_cvt_pk_bf16_f32 v80, v74, v75
	v_or_b32_e32 v74, 48, v150
	global_store_dwordx4 v[66:67], v[44:47], off offset:256 nt
	v_cvt_pk_bf16_f32 v31, v26, v27
	v_mad_i64_i32 v[24:25], s[0:1], v24, s91, v[146:147]
	v_lshl_add_u64 v[44:45], v[40:41], 0, v[144:145]
	v_cvt_pk_bf16_f32 v12, v12, v13
	v_cvt_pk_bf16_f32 v13, v14, v15
	v_cvt_pk_bf16_f32 v14, v8, v9
	v_add_u32_e32 v8, 0xb0, v150
	global_store_dwordx4 v[110:111], v[94:97], off offset:256 nt
	v_cvt_pk_bf16_f32 v81, v76, v77
	v_mad_i64_i32 v[74:75], s[0:1], v74, s91, v[146:147]
	v_lshl_add_u64 v[94:95], v[90:91], 0, v[144:145]
	global_store_dwordx4 v[44:45], v[28:31], off offset:256 nt
	v_cvt_pk_bf16_f32 v15, v10, v11
	v_mad_i64_i32 v[8:9], s[0:1], v8, s91, v[146:147]
	v_lshl_add_u64 v[28:29], v[24:25], 0, v[144:145]
	v_cvt_pk_bf16_f32 v126, v126, v127
	v_cvt_pk_bf16_f32 v127, v128, v129
	v_cvt_pk_bf16_f32 v128, v122, v123
	v_cvt_pk_bf16_f32 v129, v124, v125
	v_cvt_pk_bf16_f32 v106, v118, v119
	v_cvt_pk_bf16_f32 v107, v120, v121
	v_cvt_pk_bf16_f32 v108, v114, v115
	v_cvt_pk_bf16_f32 v109, v116, v117
	v_cvt_pk_bf16_f32 v90, v102, v103
	v_cvt_pk_bf16_f32 v91, v104, v105
	v_cvt_pk_bf16_f32 v92, v98, v99
	v_cvt_pk_bf16_f32 v93, v100, v101
	global_store_dwordx4 v[94:95], v[78:81], off offset:256 nt
	v_cvt_pk_bf16_f32 v76, v82, v83
	v_cvt_pk_bf16_f32 v77, v84, v85
	v_lshl_add_u64 v[78:79], v[74:75], 0, v[144:145]
	v_cvt_pk_bf16_f32 v74, v86, v87
	v_cvt_pk_bf16_f32 v75, v88, v89
	v_cvt_pk_bf16_f32 v73, v68, v69
	v_cvt_pk_bf16_f32 v60, v60, v61
	v_cvt_pk_bf16_f32 v61, v62, v63
	v_cvt_pk_bf16_f32 v62, v56, v57
	v_cvt_pk_bf16_f32 v63, v58, v59
	v_cvt_pk_bf16_f32 v40, v52, v53
	v_cvt_pk_bf16_f32 v41, v54, v55
	v_cvt_pk_bf16_f32 v42, v48, v49
	v_cvt_pk_bf16_f32 v43, v50, v51
	v_cvt_pk_bf16_f32 v24, v36, v37
	v_cvt_pk_bf16_f32 v25, v38, v39
	v_cvt_pk_bf16_f32 v26, v32, v33
	v_cvt_pk_bf16_f32 v27, v34, v35
	global_store_dwordx4 v[28:29], v[12:15], off offset:256 nt
	v_cvt_pk_bf16_f32 v10, v16, v17
	v_cvt_pk_bf16_f32 v11, v18, v19
	v_lshl_add_u64 v[12:13], v[8:9], 0, v[144:145]
	v_cvt_pk_bf16_f32 v8, v20, v21
	v_cvt_pk_bf16_f32 v9, v22, v23
	v_cvt_pk_bf16_f32 v4, v4, v5
	v_cvt_pk_bf16_f32 v5, v6, v7
	v_cvt_pk_bf16_f32 v6, v0, v1
	v_cvt_pk_bf16_f32 v7, v2, v3
	s_andn2_b64 vcc, exec, s[2:3]
	s_mov_b64 s[0:1], -1
	s_mov_b64 s[36:37], 0x80
	global_store_dwordx4 v[148:149], v[126:129], off nt
	global_store_dwordx4 v[110:111], v[106:109], off nt
	global_store_dwordx4 v[94:95], v[90:93], off nt
	global_store_dwordx4 v[78:79], v[74:77], off nt
	global_store_dwordx4 v[78:79], v[70:73], off offset:256 nt
	global_store_dwordx4 v[66:67], v[60:63], off nt
	global_store_dwordx4 v[44:45], v[40:43], off nt
	global_store_dwordx4 v[28:29], v[24:27], off nt
	global_store_dwordx4 v[12:13], v[8:11], off nt
	global_store_dwordx4 v[12:13], v[4:7], off offset:256 nt
	s_cbranch_vccnz .LBB0_308
	s_andn2_b64 vcc, exec, s[4:5]
	s_cbranch_vccnz .LBB0_307
	s_barrier
	s_branch .LBB0_307
